# adaLN modulation main loop: two iterations' weight loads (16) issued per round trip via a second register set (8 load round trips instead of 16)
# speedup vs baseline: 1.0074x; 1.0024x over previous
.LBB0_13:
	v_add_co_u32_e32 v18, vcc, 0xffeb0000, v8
	v_add_u32_e32 v31, 0x1000, v28
	s_nop 0
	v_addc_co_u32_e32 v19, vcc, -1, v9, vcc
	v_add_u32_e32 v78, 0x2000, v28
	v_add_u32_e32 v80, 0x3000, v28
	v_add_u32_e32 v82, 0x4000, v28
	v_add_u32_e32 v84, 0x5000, v28
	v_add_u32_e32 v86, 0x6000, v28
	v_add_u32_e32 v88, 0x7000, v28
	v_add_u32_e32 v94, 0x8000, v28
	v_add_co_u32_e32 v30, vcc, 0xffee0000, v8
	ds_read2_b32 v[22:23], v28 offset1:8
	ds_read2_b32 v[20:21], v28 offset0:16 offset1:24
	ds_read2_b32 v[24:25], v28 offset0:32 offset1:40
	ds_read2_b32 v[26:27], v28 offset0:48 offset1:56
	ds_read2_b32 v[32:33], v31 offset1:8
	ds_read2_b32 v[34:35], v78 offset1:8
	ds_read2_b32 v[36:37], v80 offset1:8
	ds_read2_b32 v[38:39], v82 offset1:8
	ds_read2_b32 v[40:41], v84 offset1:8
	ds_read2_b32 v[42:43], v86 offset1:8
	ds_read2_b32 v[44:45], v88 offset1:8
	ds_read2_b32 v[46:47], v94 offset1:8
	ds_read2_b32 v[48:49], v31 offset0:16 offset1:24
	ds_read2_b32 v[50:51], v78 offset0:16 offset1:24
	ds_read2_b32 v[52:53], v80 offset0:16 offset1:24
	ds_read2_b32 v[54:55], v82 offset0:16 offset1:24
	ds_read2_b32 v[56:57], v84 offset0:16 offset1:24
	ds_read2_b32 v[58:59], v86 offset0:16 offset1:24
	ds_read2_b32 v[60:61], v88 offset0:16 offset1:24
	ds_read2_b32 v[62:63], v31 offset0:32 offset1:40
	ds_read2_b32 v[64:65], v78 offset0:32 offset1:40
	ds_read2_b32 v[66:67], v80 offset0:32 offset1:40
	ds_read2_b32 v[68:69], v82 offset0:32 offset1:40
	ds_read2_b32 v[70:71], v84 offset0:32 offset1:40
	ds_read2_b32 v[72:73], v86 offset0:32 offset1:40
	ds_read2_b32 v[74:75], v88 offset0:32 offset1:40
	ds_read2_b32 v[76:77], v31 offset0:48 offset1:56
	ds_read2_b32 v[78:79], v78 offset0:48 offset1:56
	ds_read2_b32 v[80:81], v80 offset0:48 offset1:56
	ds_read2_b32 v[82:83], v82 offset0:48 offset1:56
	ds_read2_b32 v[84:85], v84 offset0:48 offset1:56
	ds_read2_b32 v[86:87], v86 offset0:48 offset1:56
	ds_read2_b32 v[88:89], v88 offset0:48 offset1:56
	ds_read2_b32 v[90:91], v94 offset0:16 offset1:24
	ds_read2_b32 v[92:93], v94 offset0:32 offset1:40
	ds_read2_b32 v[94:95], v94 offset0:48 offset1:56
	v_addc_co_u32_e32 v31, vcc, -1, v9, vcc
	v_add_co_u32_e32 v96, vcc, 0xfff10000, v8
	global_load_dword v98, v[18:19], off
	global_load_dword v99, v[30:31], off
	v_addc_co_u32_e32 v97, vcc, -1, v9, vcc
	v_add_co_u32_e32 v18, vcc, 0xfff40000, v8
	s_waitcnt lgkmcnt(14)
	v_mov_b32_e32 v102, v34
	v_addc_co_u32_e32 v19, vcc, -1, v9, vcc
	v_add_co_u32_e32 v30, vcc, 0xfff70000, v8
	global_load_dword v100, v[96:97], off
	global_load_dword v101, v[18:19], off
	v_addc_co_u32_e32 v31, vcc, -1, v9, vcc
	v_add_co_u32_e32 v18, vcc, 0xfffa0000, v8
	v_mov_b32_e32 v96, v22
	s_nop 0
	v_addc_co_u32_e32 v19, vcc, -1, v9, vcc
	v_add_co_u32_e32 v104, vcc, 0xfffd0000, v8
	global_load_dword v106, v[30:31], off
	global_load_dword v107, v[18:19], off
	v_addc_co_u32_e32 v105, vcc, -1, v9, vcc
	v_mov_b32_e32 v22, v20
	v_mov_b32_e32 v20, v24
	v_mov_b32_e32 v24, v26
	global_load_dword v18, v[104:105], off
	global_load_dword v26, v[8:9], off
	s_mov_b64 s[16:17], 0x30000
	v_lshl_add_u64 v[118:119], v[8:9], 0, s[16:17]
	global_load_dword v120, v[118:119], off
	v_lshl_add_u64 v[118:119], v[118:119], 0, s[16:17]
	global_load_dword v121, v[118:119], off
	v_lshl_add_u64 v[118:119], v[118:119], 0, s[16:17]
	global_load_dword v122, v[118:119], off
	v_lshl_add_u64 v[118:119], v[118:119], 0, s[16:17]
	global_load_dword v123, v[118:119], off
	v_lshl_add_u64 v[118:119], v[118:119], 0, s[16:17]
	global_load_dword v124, v[118:119], off
	v_lshl_add_u64 v[118:119], v[118:119], 0, s[16:17]
	global_load_dword v125, v[118:119], off
	v_lshl_add_u64 v[118:119], v[118:119], 0, s[16:17]
	global_load_dword v126, v[118:119], off
	v_lshl_add_u64 v[118:119], v[118:119], 0, s[16:17]
	global_load_dword v127, v[118:119], off
	v_mov_b32_e32 v97, v32
	v_mov_b32_e32 v103, v36
	v_mov_b32_e32 v36, v35
	v_mov_b32_e32 v34, v38
	v_mov_b32_e32 v35, v40
	v_mov_b32_e32 v40, v39
	v_mov_b32_e32 v38, v42
	v_mov_b32_e32 v39, v44
	v_mov_b32_e32 v32, v23
	v_mov_b32_e32 v44, v43
	v_mov_b32_e32 v23, v48
	v_mov_b32_e32 v30, v50
	v_mov_b32_e32 v31, v52
	v_mov_b32_e32 v52, v51
	v_mov_b32_e32 v42, v54
	v_mov_b32_e32 v43, v56
	v_mov_b32_e32 v50, v58
	v_mov_b32_e32 v51, v60
	v_mov_b32_e32 v48, v21
	v_mov_b32_e32 v56, v55
	v_mov_b32_e32 v60, v59
	v_mov_b32_e32 v21, v62
	v_mov_b32_e32 v54, v64
	v_mov_b32_e32 v55, v66
	v_mov_b32_e32 v66, v65
	s_waitcnt lgkmcnt(8)
	v_mov_b32_e32 v58, v78
	s_waitcnt lgkmcnt(7)
	v_mov_b32_e32 v59, v80
	v_mov_b32_e32 v80, v79
	v_mov_b32_e32 v64, v68
	v_mov_b32_e32 v65, v70
	v_mov_b32_e32 v78, v72
	v_mov_b32_e32 v79, v74
	v_mov_b32_e32 v62, v25
	v_mov_b32_e32 v70, v69
	v_mov_b32_e32 v74, v73
	v_mov_b32_e32 v25, v76
	s_waitcnt lgkmcnt(6)
	v_mov_b32_e32 v68, v82
	s_waitcnt lgkmcnt(5)
	v_mov_b32_e32 v69, v84
	s_waitcnt lgkmcnt(4)
	v_mov_b32_e32 v72, v86
	s_waitcnt lgkmcnt(3)
	v_mov_b32_e32 v73, v88
	v_add_u32_e32 v7, 64, v7
	v_cmp_lt_u32_e64 s[6:7], s15, v7
	v_mov_b32_e32 v76, v27
	v_mov_b32_e32 v84, v83
	v_mov_b32_e32 v88, v87
	v_add_u32_e32 v28, 0x100, v28
	s_or_b64 s[10:11], s[6:7], s[10:11]
	v_lshl_add_u64 v[8:9], v[8:9], 0, s[12:13]
	s_waitcnt vmcnt(6)
	v_pk_fma_f32 v[10:11], v[98:99], v[96:97], v[10:11] op_sel_hi:[0,1,1]
	v_pk_fma_f32 v[12:13], v[98:99], v[102:103], v[12:13] op_sel_hi:[0,1,1]
	v_pk_fma_f32 v[14:15], v[98:99], v[34:35], v[14:15] op_sel_hi:[0,1,1]
	v_pk_fma_f32 v[16:17], v[98:99], v[38:39], v[16:17] op_sel_hi:[0,1,1]
	v_mov_b32_e32 v34, v99
	v_pk_mul_f32 v[38:39], v[98:99], v[46:47]
	v_pk_fma_f32 v[10:11], v[34:35], v[32:33], v[10:11] op_sel_hi:[0,1,1]
	v_pk_fma_f32 v[12:13], v[34:35], v[36:37], v[12:13] op_sel_hi:[0,1,1]
	v_pk_fma_f32 v[14:15], v[34:35], v[40:41], v[14:15] op_sel_hi:[0,1,1]
	v_pk_fma_f32 v[16:17], v[34:35], v[44:45], v[16:17] op_sel_hi:[0,1,1]
	v_add_f32_e32 v19, v29, v38
	s_waitcnt vmcnt(4)
	v_pk_fma_f32 v[10:11], v[100:101], v[22:23], v[10:11] op_sel_hi:[0,1,1]
	v_pk_fma_f32 v[12:13], v[100:101], v[30:31], v[12:13] op_sel_hi:[0,1,1]
	v_pk_fma_f32 v[14:15], v[100:101], v[42:43], v[14:15] op_sel_hi:[0,1,1]
	v_pk_fma_f32 v[16:17], v[100:101], v[50:51], v[16:17] op_sel_hi:[0,1,1]
	v_mov_b32_e32 v22, v101
	v_add_f32_e32 v19, v19, v39
	s_waitcnt lgkmcnt(2)
	v_pk_mul_f32 v[30:31], v[100:101], v[90:91]
	v_pk_fma_f32 v[10:11], v[22:23], v[48:49], v[10:11] op_sel_hi:[0,1,1]
	v_pk_fma_f32 v[12:13], v[22:23], v[52:53], v[12:13] op_sel_hi:[0,1,1]
	v_pk_fma_f32 v[14:15], v[22:23], v[56:57], v[14:15] op_sel_hi:[0,1,1]
	v_pk_fma_f32 v[16:17], v[22:23], v[60:61], v[16:17] op_sel_hi:[0,1,1]
	v_add_f32_e32 v19, v19, v30
	v_add_f32_e32 v19, v19, v31
	s_waitcnt vmcnt(2) lgkmcnt(1)
	v_pk_mul_f32 v[22:23], v[106:107], v[92:93]
	v_pk_fma_f32 v[10:11], v[106:107], v[20:21], v[10:11] op_sel_hi:[0,1,1]
	v_mov_b32_e32 v20, v107
	v_pk_fma_f32 v[12:13], v[106:107], v[54:55], v[12:13] op_sel_hi:[0,1,1]
	v_pk_fma_f32 v[14:15], v[106:107], v[64:65], v[14:15] op_sel_hi:[0,1,1]
	v_pk_fma_f32 v[16:17], v[106:107], v[78:79], v[16:17] op_sel_hi:[0,1,1]
	v_add_f32_e32 v19, v19, v22
	v_pk_fma_f32 v[10:11], v[20:21], v[62:63], v[10:11] op_sel_hi:[0,1,1]
	v_pk_fma_f32 v[12:13], v[20:21], v[66:67], v[12:13] op_sel_hi:[0,1,1]
	v_pk_fma_f32 v[14:15], v[20:21], v[70:71], v[14:15] op_sel_hi:[0,1,1]
	v_pk_fma_f32 v[16:17], v[20:21], v[74:75], v[16:17] op_sel_hi:[0,1,1]
	v_add_f32_e32 v20, v19, v23
	s_waitcnt vmcnt(1)
	v_pk_fma_f32 v[10:11], v[18:19], v[24:25], v[10:11] op_sel_hi:[0,1,1]
	v_pk_fma_f32 v[12:13], v[18:19], v[58:59], v[12:13] op_sel_hi:[0,1,1]
	v_pk_fma_f32 v[14:15], v[18:19], v[68:69], v[14:15] op_sel_hi:[0,1,1]
	v_pk_fma_f32 v[16:17], v[18:19], v[72:73], v[16:17] op_sel_hi:[0,1,1]
	s_waitcnt vmcnt(0)
	v_mov_b32_e32 v19, v26
	s_waitcnt lgkmcnt(0)
	v_pk_mul_f32 v[18:19], v[18:19], v[94:95]
	v_pk_fma_f32 v[10:11], v[26:27], v[76:77], v[10:11] op_sel_hi:[0,1,1]
	v_add_f32_e32 v18, v20, v18
	v_pk_fma_f32 v[12:13], v[26:27], v[80:81], v[12:13] op_sel_hi:[0,1,1]
	v_pk_fma_f32 v[14:15], v[26:27], v[84:85], v[14:15] op_sel_hi:[0,1,1]
	v_pk_fma_f32 v[16:17], v[26:27], v[88:89], v[16:17] op_sel_hi:[0,1,1]
	v_add_f32_e32 v29, v18, v19
	s_andn2_b64 exec, exec, s[10:11]
	s_cbranch_execz .Lmod_exit
.Lmod_odd:
	v_add_co_u32_e32 v18, vcc, 0xffeb0000, v8
	v_add_u32_e32 v31, 0x1000, v28
	s_nop 0
	v_addc_co_u32_e32 v19, vcc, -1, v9, vcc
	v_add_u32_e32 v78, 0x2000, v28
	v_add_u32_e32 v80, 0x3000, v28
	v_add_u32_e32 v82, 0x4000, v28
	v_add_u32_e32 v84, 0x5000, v28
	v_add_u32_e32 v86, 0x6000, v28
	v_add_u32_e32 v88, 0x7000, v28
	v_add_u32_e32 v94, 0x8000, v28
	v_add_co_u32_e32 v30, vcc, 0xffee0000, v8
	ds_read2_b32 v[22:23], v28 offset1:8
	ds_read2_b32 v[20:21], v28 offset0:16 offset1:24
	ds_read2_b32 v[24:25], v28 offset0:32 offset1:40
	ds_read2_b32 v[26:27], v28 offset0:48 offset1:56
	ds_read2_b32 v[32:33], v31 offset1:8
	ds_read2_b32 v[34:35], v78 offset1:8
	ds_read2_b32 v[36:37], v80 offset1:8
	ds_read2_b32 v[38:39], v82 offset1:8
	ds_read2_b32 v[40:41], v84 offset1:8
	ds_read2_b32 v[42:43], v86 offset1:8
	ds_read2_b32 v[44:45], v88 offset1:8
	ds_read2_b32 v[46:47], v94 offset1:8
	ds_read2_b32 v[48:49], v31 offset0:16 offset1:24
	ds_read2_b32 v[50:51], v78 offset0:16 offset1:24
	ds_read2_b32 v[52:53], v80 offset0:16 offset1:24
	ds_read2_b32 v[54:55], v82 offset0:16 offset1:24
	ds_read2_b32 v[56:57], v84 offset0:16 offset1:24
	ds_read2_b32 v[58:59], v86 offset0:16 offset1:24
	ds_read2_b32 v[60:61], v88 offset0:16 offset1:24
	ds_read2_b32 v[62:63], v31 offset0:32 offset1:40
	ds_read2_b32 v[64:65], v78 offset0:32 offset1:40
	ds_read2_b32 v[66:67], v80 offset0:32 offset1:40
	ds_read2_b32 v[68:69], v82 offset0:32 offset1:40
	ds_read2_b32 v[70:71], v84 offset0:32 offset1:40
	ds_read2_b32 v[72:73], v86 offset0:32 offset1:40
	ds_read2_b32 v[74:75], v88 offset0:32 offset1:40
	ds_read2_b32 v[76:77], v31 offset0:48 offset1:56
	ds_read2_b32 v[78:79], v78 offset0:48 offset1:56
	ds_read2_b32 v[80:81], v80 offset0:48 offset1:56
	ds_read2_b32 v[82:83], v82 offset0:48 offset1:56
	ds_read2_b32 v[84:85], v84 offset0:48 offset1:56
	ds_read2_b32 v[86:87], v86 offset0:48 offset1:56
	ds_read2_b32 v[88:89], v88 offset0:48 offset1:56
	ds_read2_b32 v[90:91], v94 offset0:16 offset1:24
	ds_read2_b32 v[92:93], v94 offset0:32 offset1:40
	ds_read2_b32 v[94:95], v94 offset0:48 offset1:56
	v_addc_co_u32_e32 v31, vcc, -1, v9, vcc
	v_add_co_u32_e32 v96, vcc, 0xfff10000, v8
	v_mov_b32_e32 v98, v120
	v_mov_b32_e32 v99, v121
	v_addc_co_u32_e32 v97, vcc, -1, v9, vcc
	v_add_co_u32_e32 v18, vcc, 0xfff40000, v8
	s_waitcnt lgkmcnt(14)
	v_mov_b32_e32 v102, v34
	v_addc_co_u32_e32 v19, vcc, -1, v9, vcc
	v_add_co_u32_e32 v30, vcc, 0xfff70000, v8
	v_mov_b32_e32 v100, v122
	v_mov_b32_e32 v101, v123
	v_addc_co_u32_e32 v31, vcc, -1, v9, vcc
	v_add_co_u32_e32 v18, vcc, 0xfffa0000, v8
	v_mov_b32_e32 v96, v22
	s_nop 0
	v_addc_co_u32_e32 v19, vcc, -1, v9, vcc
	v_add_co_u32_e32 v104, vcc, 0xfffd0000, v8
	v_mov_b32_e32 v106, v124
	v_mov_b32_e32 v107, v125
	v_addc_co_u32_e32 v105, vcc, -1, v9, vcc
	v_mov_b32_e32 v22, v20
	v_mov_b32_e32 v20, v24
	v_mov_b32_e32 v24, v26
	v_mov_b32_e32 v18, v126
	v_mov_b32_e32 v26, v127
	v_mov_b32_e32 v97, v32
	v_mov_b32_e32 v103, v36
	v_mov_b32_e32 v36, v35
	v_mov_b32_e32 v34, v38
	v_mov_b32_e32 v35, v40
	v_mov_b32_e32 v40, v39
	v_mov_b32_e32 v38, v42
	v_mov_b32_e32 v39, v44
	v_mov_b32_e32 v32, v23
	v_mov_b32_e32 v44, v43
	v_mov_b32_e32 v23, v48
	v_mov_b32_e32 v30, v50
	v_mov_b32_e32 v31, v52
	v_mov_b32_e32 v52, v51
	v_mov_b32_e32 v42, v54
	v_mov_b32_e32 v43, v56
	v_mov_b32_e32 v50, v58
	v_mov_b32_e32 v51, v60
	v_mov_b32_e32 v48, v21
	v_mov_b32_e32 v56, v55
	v_mov_b32_e32 v60, v59
	v_mov_b32_e32 v21, v62
	v_mov_b32_e32 v54, v64
	v_mov_b32_e32 v55, v66
	v_mov_b32_e32 v66, v65
	s_waitcnt lgkmcnt(8)
	v_mov_b32_e32 v58, v78
	s_waitcnt lgkmcnt(7)
	v_mov_b32_e32 v59, v80
	v_mov_b32_e32 v80, v79
	v_mov_b32_e32 v64, v68
	v_mov_b32_e32 v65, v70
	v_mov_b32_e32 v78, v72
	v_mov_b32_e32 v79, v74
	v_mov_b32_e32 v62, v25
	v_mov_b32_e32 v70, v69
	v_mov_b32_e32 v74, v73
	v_mov_b32_e32 v25, v76
	s_waitcnt lgkmcnt(6)
	v_mov_b32_e32 v68, v82
	s_waitcnt lgkmcnt(5)
	v_mov_b32_e32 v69, v84
	s_waitcnt lgkmcnt(4)
	v_mov_b32_e32 v72, v86
	s_waitcnt lgkmcnt(3)
	v_mov_b32_e32 v73, v88
	v_add_u32_e32 v7, 64, v7
	v_cmp_lt_u32_e64 s[6:7], s15, v7
	v_mov_b32_e32 v76, v27
	v_mov_b32_e32 v84, v83
	v_mov_b32_e32 v88, v87
	v_add_u32_e32 v28, 0x100, v28
	s_or_b64 s[10:11], s[6:7], s[10:11]
	v_lshl_add_u64 v[8:9], v[8:9], 0, s[12:13]
	s_waitcnt vmcnt(6)
	v_pk_fma_f32 v[10:11], v[98:99], v[96:97], v[10:11] op_sel_hi:[0,1,1]
	v_pk_fma_f32 v[12:13], v[98:99], v[102:103], v[12:13] op_sel_hi:[0,1,1]
	v_pk_fma_f32 v[14:15], v[98:99], v[34:35], v[14:15] op_sel_hi:[0,1,1]
	v_pk_fma_f32 v[16:17], v[98:99], v[38:39], v[16:17] op_sel_hi:[0,1,1]
	v_mov_b32_e32 v34, v99
	v_pk_mul_f32 v[38:39], v[98:99], v[46:47]
	v_pk_fma_f32 v[10:11], v[34:35], v[32:33], v[10:11] op_sel_hi:[0,1,1]
	v_pk_fma_f32 v[12:13], v[34:35], v[36:37], v[12:13] op_sel_hi:[0,1,1]
	v_pk_fma_f32 v[14:15], v[34:35], v[40:41], v[14:15] op_sel_hi:[0,1,1]
	v_pk_fma_f32 v[16:17], v[34:35], v[44:45], v[16:17] op_sel_hi:[0,1,1]
	v_add_f32_e32 v19, v29, v38
	s_waitcnt vmcnt(4)
	v_pk_fma_f32 v[10:11], v[100:101], v[22:23], v[10:11] op_sel_hi:[0,1,1]
	v_pk_fma_f32 v[12:13], v[100:101], v[30:31], v[12:13] op_sel_hi:[0,1,1]
	v_pk_fma_f32 v[14:15], v[100:101], v[42:43], v[14:15] op_sel_hi:[0,1,1]
	v_pk_fma_f32 v[16:17], v[100:101], v[50:51], v[16:17] op_sel_hi:[0,1,1]
	v_mov_b32_e32 v22, v101
	v_add_f32_e32 v19, v19, v39
	s_waitcnt lgkmcnt(2)
	v_pk_mul_f32 v[30:31], v[100:101], v[90:91]
	v_pk_fma_f32 v[10:11], v[22:23], v[48:49], v[10:11] op_sel_hi:[0,1,1]
	v_pk_fma_f32 v[12:13], v[22:23], v[52:53], v[12:13] op_sel_hi:[0,1,1]
	v_pk_fma_f32 v[14:15], v[22:23], v[56:57], v[14:15] op_sel_hi:[0,1,1]
	v_pk_fma_f32 v[16:17], v[22:23], v[60:61], v[16:17] op_sel_hi:[0,1,1]
	v_add_f32_e32 v19, v19, v30
	v_add_f32_e32 v19, v19, v31
	s_waitcnt vmcnt(2) lgkmcnt(1)
	v_pk_mul_f32 v[22:23], v[106:107], v[92:93]
	v_pk_fma_f32 v[10:11], v[106:107], v[20:21], v[10:11] op_sel_hi:[0,1,1]
	v_mov_b32_e32 v20, v107
	v_pk_fma_f32 v[12:13], v[106:107], v[54:55], v[12:13] op_sel_hi:[0,1,1]
	v_pk_fma_f32 v[14:15], v[106:107], v[64:65], v[14:15] op_sel_hi:[0,1,1]
	v_pk_fma_f32 v[16:17], v[106:107], v[78:79], v[16:17] op_sel_hi:[0,1,1]
	v_add_f32_e32 v19, v19, v22
	v_pk_fma_f32 v[10:11], v[20:21], v[62:63], v[10:11] op_sel_hi:[0,1,1]
	v_pk_fma_f32 v[12:13], v[20:21], v[66:67], v[12:13] op_sel_hi:[0,1,1]
	v_pk_fma_f32 v[14:15], v[20:21], v[70:71], v[14:15] op_sel_hi:[0,1,1]
	v_pk_fma_f32 v[16:17], v[20:21], v[74:75], v[16:17] op_sel_hi:[0,1,1]
	v_add_f32_e32 v20, v19, v23
	s_waitcnt vmcnt(1)
	v_pk_fma_f32 v[10:11], v[18:19], v[24:25], v[10:11] op_sel_hi:[0,1,1]
	v_pk_fma_f32 v[12:13], v[18:19], v[58:59], v[12:13] op_sel_hi:[0,1,1]
	v_pk_fma_f32 v[14:15], v[18:19], v[68:69], v[14:15] op_sel_hi:[0,1,1]
	v_pk_fma_f32 v[16:17], v[18:19], v[72:73], v[16:17] op_sel_hi:[0,1,1]
	s_waitcnt vmcnt(0)
	v_mov_b32_e32 v19, v26
	s_waitcnt lgkmcnt(0)
	v_pk_mul_f32 v[18:19], v[18:19], v[94:95]
	v_pk_fma_f32 v[10:11], v[26:27], v[76:77], v[10:11] op_sel_hi:[0,1,1]
	v_add_f32_e32 v18, v20, v18
	v_pk_fma_f32 v[12:13], v[26:27], v[80:81], v[12:13] op_sel_hi:[0,1,1]
	v_pk_fma_f32 v[14:15], v[26:27], v[84:85], v[14:15] op_sel_hi:[0,1,1]
	v_pk_fma_f32 v[16:17], v[26:27], v[88:89], v[16:17] op_sel_hi:[0,1,1]
	v_add_f32_e32 v29, v18, v19
	s_andn2_b64 exec, exec, s[10:11]
	s_cbranch_execnz .LBB0_13
.Lmod_exit:
	s_or_b64 exec, exec, s[10:11]
	v_lshlrev_b32_e32 v8, 2, v6
	v_mul_u32_u24_e32 v6, 0x900, v1
	s_movk_i32 s6, 0x240
	v_add3_u32 v6, 0, v8, v6
	v_cmp_gt_u32_e32 vcc, s6, v246
	ds_write2st64_b32 v6, v10, v11 offset0:144 offset1:145
	ds_write2st64_b32 v6, v12, v13 offset0:146 offset1:147
	ds_write2st64_b32 v6, v14, v15 offset0:148 offset1:149
	ds_write2st64_b32 v6, v16, v17 offset0:150 offset1:151
	ds_write_b32 v6, v29 offset:38912
	s_waitcnt lgkmcnt(0)
	s_barrier
	s_and_saveexec_b64 s[6:7], vcc
	s_cbranch_execz .LBB0_17
	s_load_dwordx2 s[10:11], s[84:85], 0x28
	s_mul_hi_i32 s12, s14, 0x36000
	s_mul_i32 s13, s14, 0x36000
	s_mul_hi_i32 s15, s14, 0x6000
	s_mulk_i32 s14, 0x6000
	s_waitcnt lgkmcnt(0)
	s_add_u32 s10, s10, s14
	s_addc_u32 s11, s11, s15
	s_add_u32 s10, s10, s8
	s_addc_u32 s11, s11, s9
	s_add_u32 s8, s8, s13
	s_addc_u32 s9, s9, s12
	v_lshl_add_u64 v[4:5], s[8:9], 0, v[4:5]
	v_lshl_add_u64 v[2:3], v[4:5], 0, v[2:3]
	v_lshl_or_b32 v1, v1, 8, v8
	v_mov_b32_e32 v9, 0
	v_lshl_add_u64 v[2:3], s[88:89], 0, v[2:3]
	s_mov_b64 s[8:9], 0x100000
	v_add_u32_e32 v1, 0, v1
	v_lshl_add_u64 v[6:7], s[10:11], 0, v[8:9]
	v_add_u32_e32 v9, 0xfffffe00, v246
	v_lshl_add_u64 v[2:3], v[2:3], 0, s[8:9]
	v_add_u32_e32 v1, 0x9000, v1
	s_mov_b64 s[8:9], 0
	s_mov_b64 s[10:11], 0x30000
